# GEMM phase prologue: K-tile 1 LDS-DMA requested together with K-tile 0 (one round trip less before the first MFMA of each phase)
# baseline (speedup 1.0000x reference)
; #define PG8_STAGE(bufoff, gbase, voff) do { _Pragma("unroll") for (int _i = 0; _i < 2; ++_i) \
;         __builtin_amdgcn_global_load_lds((const unsigned*)((const char*)(gbase) + (voff)[_i]), (PG8_LAS unsigned*)(lds + (bufoff) + ldsw + _i * 8192), 16, 0, 0); } while (0)
; #define PG8_WAIT_V(n) asm volatile("s_waitcnt vmcnt(" #n ")" ::: "memory")
; #define PG8_BAR __builtin_amdgcn_s_barrier()
; template <class Epi, class Sched, bool ALIGN_EPI = false, bool SP2 = false>
; __device__ __forceinline__ void gemm_phase(PG8_LAS unsigned char* lds, const Gemm g, const Sched& S, const Epi& E) {
;     ...
;         PG8_STAGE(PG8_SB(0, 0), cB, voffB); PG8_STAGE(PG8_SB(0, 1), cB + hstepB, voffB); PG8_STAGE(PG8_SA(0, 0), cA, voffA); PG8_STAGE(PG8_SA(0, 1), cA + hstepA, voffA);
;         if (wr == 1) PG8_BAR;
;         PG8_WAIT_V(2); PG8_BAR;
;         PG8_STAGE(PG8_SB(1, 0), cB + kstep, voffB); PG8_STAGE(PG8_SA(1, 0), cA + kstep, voffA); PG8_STAGE(PG8_SB(1, 1), cB + hstepB + kstep, voffB);
;         PG8_WAIT_V(6); PG8_BAR;
.LBB0_150:
	s_add_u32 s12, s6, 0x7a00000
	s_addc_u32 s13, s7, 0
	s_lshl_b32 s8, s15, 5
	s_add_i32 s49, s1, 0x18000
	s_and_b32 s17, s8, 0x60
	s_add_i32 s50, s49, s2
	s_lshl_b32 s16, s14, 13
	s_lshl_b32 s15, s17, 7
	v_lshl_add_u64 v[6:7], v[6:7], 0, s[76:77]
	s_mov_b32 m0, s50
	s_add_i32 s51, s50, 0x2000
	s_add_i32 s60, s43, 0x8000
	s_add_i32 s61, s43, 0xa000
	global_load_lds_dwordx4 v[6:7], off
	v_lshl_add_u64 v[4:5], v[4:5], 0, s[76:77]
	s_mov_b32 m0, s51
	s_add_u32 s8, s26, 0x40080
	global_load_lds_dwordx4 v[4:5], off
	v_lshl_add_u64 v[0:1], v[0:1], 0, s[76:77]
	s_mov_b32 m0, s60
	s_addc_u32 s9, s27, 0
	s_add_i32 s64, s1, 0x1c000
	global_load_lds_dwordx4 v[0:1], off
	v_lshl_add_u64 v[0:1], v[2:3], 0, s[76:77]
	s_mov_b32 m0, s61
	s_add_i32 s65, s64, s2
	global_load_lds_dwordx4 v[0:1], off
	v_lshl_add_u64 v[0:1], s[8:9], 0, v[192:193]
	s_mov_b32 m0, s65
	s_add_i32 s66, s65, 0x2000
	global_load_lds_dwordx4 v[0:1], off
	v_lshl_add_u64 v[0:1], s[8:9], 0, v[128:129]
	s_mov_b32 m0, s66
	v_bfe_u32 v2, v9, 4, 2
	global_load_lds_dwordx4 v[0:1], off
	s_waitcnt vmcnt(8)
	s_barrier
	v_and_b32_e32 v1, 15, v9
	v_lshlrev_b32_e32 v0, 4, v2
	v_lshlrev_b32_e32 v3, 2, v9
	v_lshl_or_b32 v148, s14, 6, v1
	v_lshl_or_b32 v1, v1, 6, v0
	v_and_b32_e32 v3, 32, v3
	v_bitop3_b32 v4, v1, s16, v3 bitop3:0xde
	v_bitop3_b32 v149, v1, s15, v3 bitop3:0xde
	v_mov_b32_e32 v1, v193
	s_sext_i32_i16 s70, s4
	s_cmpk_lt_u32 s5, 0x100
	v_lshl_add_u64 v[0:1], s[6:7], 0, v[0:1]
	s_mov_b64 s[4:5], 0x3600000
	v_lshl_add_u64 v[134:135], v[0:1], 0, s[4:5]
	v_lshlrev_b32_e32 v0, 14, v8
	v_and_b32_e32 v0, 0xffff8000, v0
	v_lshl_add_u32 v0, v10, 11, v0
	v_and_b32_e32 v1, 1, v8
	v_lshl_or_b32 v0, v1, 6, v0
	v_lshl_add_u32 v136, v11, 1, v0
	v_lshlrev_b32_e32 v0, 14, v13
	v_and_b32_e32 v0, 0xffff8000, v0
	s_waitcnt vmcnt(6)
	v_lshl_add_u32 v0, v12, 11, v0
	v_and_b32_e32 v1, 1, v13
	v_lshl_or_b32 v0, v1, 6, v0
	s_cselect_b64 s[14:15], -1, 0
	s_ashr_i32 s67, s0, 31
	v_lshl_or_b32 v150, v2, 3, s17
	v_mov_b32_e32 v137, v193
	v_lshl_add_u32 v138, v14, 1, v0
	v_mov_b32_e32 v139, v193
	s_mov_b32 s68, 0
	v_add_u32_e32 v151, s1, v4
	s_barrier
	s_branch .LBB0_153

; #define PG8_STAGE(bufoff, gbase, voff) do { _Pragma("unroll") for (int _i = 0; _i < 2; ++_i) \
;         __builtin_amdgcn_global_load_lds((const unsigned*)((const char*)(gbase) + (voff)[_i]), (PG8_LAS unsigned*)(lds + (bufoff) + ldsw + _i * 8192), 16, 0, 0); } while (0)
; #define PG8_WAIT_V(n) asm volatile("s_waitcnt vmcnt(" #n ")" ::: "memory")
; #define PG8_BAR __builtin_amdgcn_s_barrier()
; template <class Epi, class Sched, bool ALIGN_EPI = false, bool SP2 = false>
; __device__ __forceinline__ void gemm_phase(PG8_LAS unsigned char* lds, const Gemm g, const Sched& S, const Epi& E) {
;     ...
;         PG8_STAGE(PG8_SB(0, 0), cB, voffB); PG8_STAGE(PG8_SB(0, 1), cB + hstepB, voffB); PG8_STAGE(PG8_SA(0, 0), cA, voffA); PG8_STAGE(PG8_SA(0, 1), cA + hstepA, voffA);
;         if (wr == 1) PG8_BAR;
;         PG8_WAIT_V(2); PG8_BAR;
;         PG8_STAGE(PG8_SB(1, 0), cB + kstep, voffB); PG8_STAGE(PG8_SA(1, 0), cA + kstep, voffA); PG8_STAGE(PG8_SB(1, 1), cB + hstepB + kstep, voffB);
;         PG8_WAIT_V(6); PG8_BAR;
; __global__ void __launch_bounds__(NTHREADS, 2) mega_fwd(Args args) {
;     ...
;             pg8::Gemm g2{(const bf16*)(ws + WS_MEMN), (const bf16*)(ws + WS_WKV), MROWS, 2 * DM, DM, DM, DM}; pg8::StaticOrder S2; S2.init(MROWS, 2 * DM, G_, bx_ >= 128 ? bx_ - 128 : (1 << 28));
;             EpiPlain E2{(bf16*)(ws + WS_KV), 2 * DM, nullptr, 1.f};
;             pg8::gemm_phase<EpiPlain, pg8::StaticOrder, true, true>(ldsp, g2, S2, E2);
.LBB0_170:
	v_bfe_u32 v16, v14, 4, 2
	s_add_u32 s6, s6, 0x3400000
	v_and_b32_e32 v15, 15, v14
	v_lshlrev_b32_e32 v17, 4, v16
	v_lshlrev_b32_e32 v14, 2, v14
	s_addc_u32 s7, s7, 0
	v_lshl_or_b32 v138, s2, 6, v15
	v_lshl_or_b32 v15, v15, 6, v17
	s_lshl_b32 s2, s2, 13
	v_and_b32_e32 v14, 32, v14
	v_bitop3_b32 v17, v15, s2, v14 bitop3:0xde
	s_lshl_b32 s2, s15, 5
	s_add_i32 s50, s1, 0x18000
	s_and_b32 s2, s2, 0x60
	s_add_i32 s51, s50, s14
	s_lshl_b32 s8, s2, 7
	v_lshl_add_u64 v[6:7], v[6:7], 0, s[76:77]
	s_mov_b32 m0, s51
	s_add_i32 s60, s51, 0x2000
	s_add_i32 s61, s44, 0x8000
	s_add_i32 s64, s44, 0xa000
	v_bitop3_b32 v139, v15, s8, v14 bitop3:0xde
	global_load_lds_dwordx4 v[6:7], off
	v_lshl_add_u64 v[4:5], v[4:5], 0, s[76:77]
	s_mov_b32 m0, s60
	s_add_u32 s8, s24, 0x40080
	global_load_lds_dwordx4 v[4:5], off
	v_lshl_add_u64 v[0:1], v[0:1], 0, s[76:77]
	s_mov_b32 m0, s61
	s_addc_u32 s9, s25, 0
	s_add_i32 s65, s1, 0x1c000
	global_load_lds_dwordx4 v[0:1], off
	v_lshl_add_u64 v[0:1], v[2:3], 0, s[76:77]
	s_mov_b32 m0, s64
	s_add_i32 s66, s65, s14
	global_load_lds_dwordx4 v[0:1], off
	v_lshl_add_u64 v[0:1], s[8:9], 0, v[192:193]
	s_mov_b32 m0, s66
	s_add_i32 s67, s66, 0x2000
	global_load_lds_dwordx4 v[0:1], off
	v_lshl_add_u64 v[0:1], s[8:9], 0, v[132:133]
	s_mov_b32 m0, s67
	s_cmpk_lt_u32 s11, 0x100
	global_load_lds_dwordx4 v[0:1], off
	s_waitcnt vmcnt(8)
	s_barrier
	v_lshlrev_b32_e32 v0, 14, v11
	v_and_b32_e32 v0, 0xffff8000, v0
	v_lshl_add_u32 v0, v12, 11, v0
	v_and_b32_e32 v1, 1, v11
	v_lshl_or_b32 v0, v1, 6, v0
	v_lshl_add_u32 v134, v13, 1, v0
	v_lshlrev_b32_e32 v0, 14, v8
	v_and_b32_e32 v0, 0xffff8000, v0
	s_waitcnt vmcnt(6)
	v_lshl_add_u32 v0, v9, 11, v0
	v_and_b32_e32 v1, 1, v8
	v_lshl_or_b32 v0, v1, 6, v0
	s_sext_i32_i8 s13, s10
	s_cselect_b64 s[10:11], -1, 0
	s_ashr_i32 s68, s0, 31
	v_lshl_or_b32 v140, v16, 3, s2
	v_mov_b32_e32 v135, v193
	v_lshl_add_u32 v136, v10, 1, v0
	v_mov_b32_e32 v137, v193
	s_mov_b32 s70, 0
	v_add_u32_e32 v141, s1, v17
	s_barrier
	s_branch .LBB0_173

; #define PG8_STAGE(bufoff, gbase, voff) do { _Pragma("unroll") for (int _i = 0; _i < 2; ++_i) \
;         __builtin_amdgcn_global_load_lds((const unsigned*)((const char*)(gbase) + (voff)[_i]), (PG8_LAS unsigned*)(lds + (bufoff) + ldsw + _i * 8192), 16, 0, 0); } while (0)
; #define PG8_WAIT_V(n) asm volatile("s_waitcnt vmcnt(" #n ")" ::: "memory")
; #define PG8_BAR __builtin_amdgcn_s_barrier()
; template <class Epi, class Sched, bool ALIGN_EPI = false, bool SP2 = false>
; __device__ __forceinline__ void gemm_phase(PG8_LAS unsigned char* lds, const Gemm g, const Sched& S, const Epi& E) {
;     ...
;         PG8_STAGE(PG8_SB(0, 0), cB, voffB); PG8_STAGE(PG8_SB(0, 1), cB + hstepB, voffB); PG8_STAGE(PG8_SA(0, 0), cA, voffA); PG8_STAGE(PG8_SA(0, 1), cA + hstepA, voffA);
;         if (wr == 1) PG8_BAR;
;         PG8_WAIT_V(2); PG8_BAR;
;         PG8_STAGE(PG8_SB(1, 0), cB + kstep, voffB); PG8_STAGE(PG8_SA(1, 0), cA + kstep, voffA); PG8_STAGE(PG8_SB(1, 1), cB + hstepB + kstep, voffB);
;         PG8_WAIT_V(6); PG8_BAR;
; __global__ void __launch_bounds__(NTHREADS, 2) mega_fwd(Args args) {
;     ...
;             pg8::Gemm g{ACT, (const bf16*)(ws + WS_W1B), M, DM, FFH, FFH, FFH}; pg8::StaticOrder S; S.init(M, DM, G_, bx_);
;             EpiRes E{XB, SSQ, 0.5f};
;             pg8::gemm_phase<EpiRes, pg8::StaticOrder, true, true>(ldsp, g, S, E);
.LBB0_264:
	s_add_u32 s12, s4, 0x3a00000
	s_addc_u32 s13, s5, 0
	s_add_u32 s14, s4, 0x3600000
	v_bfe_u32 v17, v12, 4, 2
	s_addc_u32 s15, s5, 0
	v_and_b32_e32 v18, 15, v12
	v_lshlrev_b32_e32 v20, 4, v17
	v_lshlrev_b32_e32 v12, 2, v12
	s_add_i32 s48, s18, 0x18000
	s_and_b32 s45, s6, 3
	v_lshl_or_b32 v144, s7, 6, v18
	v_lshl_or_b32 v18, v18, 6, v20
	s_lshl_b32 s4, s7, 13
	v_and_b32_e32 v12, 32, v12
	s_add_i32 s49, s48, s2
	v_bitop3_b32 v20, v18, s4, v12 bitop3:0xde
	s_lshl_b32 s4, s45, 12
	v_lshl_add_u64 v[6:7], v[6:7], 0, s[76:77]
	s_mov_b32 m0, s49
	s_add_i32 s50, s49, 0x2000
	s_add_i32 s51, s41, 0x8000
	s_add_i32 s60, s41, 0xa000
	v_bitop3_b32 v145, v18, s4, v12 bitop3:0xde
	global_load_lds_dwordx4 v[6:7], off
	v_lshl_add_u64 v[4:5], v[4:5], 0, s[76:77]
	s_mov_b32 m0, s50
	s_add_u32 s4, s22, 0xb0080
	global_load_lds_dwordx4 v[4:5], off
	v_lshl_add_u64 v[0:1], v[0:1], 0, s[76:77]
	s_mov_b32 m0, s51
	s_addc_u32 s5, s23, 0
	s_add_i32 s61, s18, 0x1c000
	global_load_lds_dwordx4 v[0:1], off
	v_lshl_add_u64 v[0:1], v[2:3], 0, s[76:77]
	s_mov_b32 m0, s60
	s_add_i32 s64, s61, s2
	global_load_lds_dwordx4 v[0:1], off
	v_lshl_add_u64 v[0:1], s[4:5], 0, v[192:193]
	s_mov_b32 m0, s64
	s_add_i32 s65, s64, 0x2000
	global_load_lds_dwordx4 v[0:1], off
	v_lshl_add_u64 v[0:1], s[4:5], 0, v[132:133]
	s_mov_b32 m0, s65
	s_movk_i32 s2, 0xb00
	global_load_lds_dwordx4 v[0:1], off
	s_waitcnt vmcnt(8)
	s_barrier
	v_lshrrev_b32_e32 v1, 1, v13
	v_mul_lo_u32 v0, v15, s2
	s_mov_b32 s8, 0xb000
	v_mad_u64_u32 v[0:1], s[6:7], v1, s8, v[0:1]
	v_or_b32_e32 v0, v0, v14
	v_add_lshl_u32 v0, v0, v16, 1
	v_mov_b32_e32 v1, v193
	s_mov_b64 s[24:25], 0xb0080
	v_lshl_add_u64 v[134:135], v[0:1], 0, s[24:25]
	v_lshrrev_b32_e32 v1, 1, v8
	v_mul_lo_u32 v0, v10, s2
	v_mad_u64_u32 v[0:1], s[6:7], v1, s8, v[0:1]
	s_waitcnt vmcnt(6)
	v_or_b32_e32 v0, v0, v9
	v_lshlrev_b32_e32 v19, 3, v17
	s_cmpk_lt_u32 s16, 0x100
	v_add_lshl_u32 v0, v0, v11, 1
	v_mov_b32_e32 v1, v193
	v_lshl_or_b32 v146, s45, 5, v19
	s_cselect_b64 s[16:17], -1, 0
	s_mov_b32 s66, 0
	v_cmp_eq_u32_e64 s[4:5], 0, v17
	s_ashr_i32 s67, s1, 31
	s_ashr_i32 s70, s0, 31
	v_lshl_add_u64 v[136:137], v[0:1], 0, s[24:25]
	v_add_u32_e32 v147, s18, v20
	s_barrier
	s_branch .LBB0_267

; #define PG8_STAGE(bufoff, gbase, voff) do { _Pragma("unroll") for (int _i = 0; _i < 2; ++_i) \
;         __builtin_amdgcn_global_load_lds((const unsigned*)((const char*)(gbase) + (voff)[_i]), (PG8_LAS unsigned*)(lds + (bufoff) + ldsw + _i * 8192), 16, 0, 0); } while (0)
; #define PG8_WAIT_V(n) asm volatile("s_waitcnt vmcnt(" #n ")" ::: "memory")
; #define PG8_BAR __builtin_amdgcn_s_barrier()
; template <class Epi, class Sched, bool ALIGN_EPI = false, bool SP2 = false>
; __device__ __forceinline__ void gemm_phase(PG8_LAS unsigned char* lds, const Gemm g, const Sched& S, const Epi& E) {
;     ...
;         PG8_STAGE(PG8_SB(0, 0), cB, voffB); PG8_STAGE(PG8_SB(0, 1), cB + hstepB, voffB); PG8_STAGE(PG8_SA(0, 0), cA, voffA); PG8_STAGE(PG8_SA(0, 1), cA + hstepA, voffA);
;         if (wr == 1) PG8_BAR;
;         PG8_WAIT_V(2); PG8_BAR;
;         PG8_STAGE(PG8_SB(1, 0), cB + kstep, voffB); PG8_STAGE(PG8_SA(1, 0), cA + kstep, voffA); PG8_STAGE(PG8_SB(1, 1), cB + hstepB + kstep, voffB);
;         PG8_WAIT_V(6); PG8_BAR;
; __global__ void __launch_bounds__(NTHREADS, 2) mega_fwd(Args args) {
;     ...
;             pg8::Gemm g{XB, (const bf16*)(ws + WS_WIN), M, NINP, DM, DM, DM}; pg8::StaticOrder S; S.init(M, NINP, G_, bx_);
;             EpiWin E{ws, (const float*)(ws + WS_LB) + l * 512, args.in[10] + l * 8};
;             pg8::gemm_phase<EpiWin, pg8::StaticOrder, true, true>(ldsp, g, S, E);
.LBB0_374:
	v_readlane_b32 s20, v255, 18
	v_readlane_b32 s21, v255, 19
	s_lshl_b32 s68, s20, 9
	s_mov_b32 s22, s20
	s_lshl_b64 s[20:21], s[68:69], 2
	s_add_u32 s1, s6, s20
	s_addc_u32 s9, s7, s21
	s_add_u32 s20, s1, 0x3700000
	s_addc_u32 s21, s9, 0
	v_writelane_b32 v255, s20, 35
	s_lshl_b32 s68, s22, 3
	v_bfe_u32 v17, v14, 4, 2
	v_writelane_b32 v255, s21, 36
	s_lshl_b64 s[20:21], s[68:69], 2
	v_readlane_b32 s22, v255, 14
	v_readlane_b32 s23, v255, 15
	s_add_u32 s34, s22, s20
	v_lshrrev_b32_e32 v15, 4, v14
	v_and_b32_e32 v16, 15, v14
	v_lshlrev_b32_e32 v192, 4, v17
	v_lshlrev_b32_e32 v14, 2, v14
	s_addc_u32 s35, s23, s21
	s_and_b32 s9, s18, 3
	v_lshl_or_b32 v172, s0, 6, v16
	v_lshl_or_b32 v16, v16, 6, v192
	s_lshl_b32 s0, s0, 13
	v_and_b32_e32 v14, 32, v14
	s_add_i32 s68, s16, 0x18000
	v_lshlrev_b32_e32 v18, 3, v17
	v_bitop3_b32 v17, v16, s0, v14 bitop3:0xde
	s_lshl_b32 s0, s9, 12
	s_add_i32 s84, s68, s2
	v_bitop3_b32 v173, v16, s0, v14 bitop3:0xde
	v_lshl_add_u64 v[6:7], v[6:7], 0, s[76:77]
	s_mov_b32 m0, s84
	s_add_i32 s64, s84, 0x2000
	s_add_i32 s65, s61, 0x8000
	s_add_i32 s0, s61, 0xa000
	global_load_lds_dwordx4 v[6:7], off
	v_lshl_add_u64 v[4:5], v[4:5], 0, s[76:77]
	s_mov_b32 m0, s64
	s_add_u32 s20, s12, 0x40080
	global_load_lds_dwordx4 v[4:5], off
	v_lshl_add_u64 v[0:1], v[0:1], 0, s[76:77]
	s_mov_b32 m0, s65
	s_addc_u32 s21, s13, 0
	s_add_i32 s1, s16, 0x1c000
	global_load_lds_dwordx4 v[0:1], off
	v_lshl_add_u64 v[0:1], v[2:3], 0, s[76:77]
	s_mov_b32 m0, s0
	s_add_i32 s48, s1, s2
	global_load_lds_dwordx4 v[0:1], off
	v_lshl_add_u64 v[0:1], s[20:21], 0, v[154:155]
	s_mov_b32 m0, s48
	s_add_i32 s49, s48, 0x2000
	global_load_lds_dwordx4 v[0:1], off
	v_lshl_add_u64 v[0:1], s[20:21], 0, v[158:159]
	s_mov_b32 m0, s49
	s_cmpk_lt_u32 s17, 0x100
	global_load_lds_dwordx4 v[0:1], off
	s_waitcnt vmcnt(8)
	s_barrier
	s_cselect_b64 s[36:37], -1, 0
	s_ashr_i32 s23, s74, 31
	s_ashr_i32 s40, s89, 31
	s_add_u32 s44, s6, 0x5a00000
	s_addc_u32 s45, s7, 0
	v_bitop3_b32 v0, s18, v15, 3 bitop3:0xa8
	s_add_u32 s18, s6, 0x7a00000
	s_addc_u32 s19, s7, 0
	v_writelane_b32 v255, s18, 37
	v_cmp_eq_u32_e64 s[38:39], 0, v0
	v_lshlrev_b32_e32 v0, 14, v11
	v_writelane_b32 v255, s19, 38
	s_add_u32 s18, s6, 0x8a00000
	s_addc_u32 s19, s7, 0
	v_writelane_b32 v255, s18, 39
	v_and_b32_e32 v0, 0xffff8000, v0
	v_lshl_add_u32 v0, v12, 11, v0
	v_writelane_b32 v255, s19, 40
	s_add_u32 s18, s6, 0xba00000
	s_addc_u32 s19, s7, 0
	v_writelane_b32 v255, s18, 41
	v_and_b32_e32 v1, 1, v11
	v_lshl_or_b32 v0, v1, 6, v0
	v_writelane_b32 v255, s19, 42
	s_add_u32 s18, s6, 0xca00000
	s_addc_u32 s19, s7, 0
	v_writelane_b32 v255, s18, 43
	v_lshl_add_u32 v162, v13, 1, v0
	v_lshlrev_b32_e32 v0, 14, v8
	v_writelane_b32 v255, s19, 44
	s_add_u32 s18, s6, 0x9a00000
	s_addc_u32 s19, s7, 0
	v_writelane_b32 v255, s18, 45
	s_add_u32 s42, s6, 0x3800000
	s_addc_u32 s43, s7, 0
	v_writelane_b32 v255, s19, 46
	v_writelane_b32 v255, s26, 31
	v_writelane_b32 v255, s30, 47
	v_and_b32_e32 v0, 0xffff8000, v0
	s_waitcnt vmcnt(6)
	s_add_u32 s82, s6, 0x3600000
	v_writelane_b32 v255, s31, 48
	v_writelane_b32 v255, s34, 49
	v_lshl_add_u32 v0, v9, 11, v0
	v_and_b32_e32 v1, 1, v8
	v_writelane_b32 v255, s35, 50
	v_writelane_b32 v255, s36, 51
	s_addc_u32 s83, s7, 0
	v_lshl_or_b32 v0, v1, 6, v0
	v_writelane_b32 v255, s37, 52
	v_writelane_b32 v255, s38, 53
	v_lshl_or_b32 v174, s9, 5, v18
	s_mov_b32 s72, 0
	v_writelane_b32 v255, s39, 54
	v_writelane_b32 v255, s23, 55
	v_writelane_b32 v255, s27, 56
	v_writelane_b32 v255, s42, 57
	v_lshl_add_u64 v[160:161], s[82:83], 0, v[192:193]
	v_mov_b32_e32 v163, v193
	v_lshl_add_u32 v164, v10, 1, v0
	v_mov_b32_e32 v165, v193
	v_add_u32_e32 v175, s16, v17
	v_writelane_b32 v255, s43, 58
	s_barrier
	s_branch .LBB0_377

; #define PG8_STAGE(bufoff, gbase, voff) do { _Pragma("unroll") for (int _i = 0; _i < 2; ++_i) \
;         __builtin_amdgcn_global_load_lds((const unsigned*)((const char*)(gbase) + (voff)[_i]), (PG8_LAS unsigned*)(lds + (bufoff) + ldsw + _i * 8192), 16, 0, 0); } while (0)
; #define PG8_WAIT_V(n) asm volatile("s_waitcnt vmcnt(" #n ")" ::: "memory")
; #define PG8_BAR __builtin_amdgcn_s_barrier()
; template <class Epi, class Sched, bool ALIGN_EPI = false, bool SP2 = false>
; __device__ __forceinline__ void gemm_phase(PG8_LAS unsigned char* lds, const Gemm g, const Sched& S, const Epi& E) {
;     ...
;     f32x4 acc[2][2][4][2];
; #pragma unroll
;     for (int a = 0; a < 2; ++a)
; #pragma unroll
;         for (int b = 0; b < 2; ++b)
; #pragma unroll
;             for (int m = 0; m < 4; ++m)
; #pragma unroll
;                 for (int n = 0; n < 2; ++n) acc[a][b][m][n] = (f32x4){0.f, 0.f, 0.f, 0.f};
;     ...
;         PG8_STAGE(PG8_SB(0, 0), cB, voffB); PG8_STAGE(PG8_SB(0, 1), cB + hstepB, voffB); PG8_STAGE(PG8_SA(0, 0), cA, voffA); PG8_STAGE(PG8_SA(0, 1), cA + hstepA, voffA);
;         if (wr == 1) PG8_BAR;
;         PG8_WAIT_V(2); PG8_BAR;
;         PG8_STAGE(PG8_SB(1, 0), cB + kstep, voffB); PG8_STAGE(PG8_SA(1, 0), cA + kstep, voffA); PG8_STAGE(PG8_SB(1, 1), cB + hstepB + kstep, voffB);
;         PG8_WAIT_V(6); PG8_BAR;
.LBB0_429:
	s_add_i32 s35, s16, 0x18000
	v_lshl_add_u64 v[2:3], s[8:9], 0, v[192:193]
	v_mov_b32_e32 v131, v193
	v_and_b32_e32 v26, 15, v0
	v_lshrrev_b32_e32 v0, 1, v0
	s_lshl_b32 s13, s13, 5
	s_add_i32 s36, s35, s2
	v_lshl_add_u64 v[4:5], s[8:9], 0, v[130:131]
	v_mov_b32_e32 v135, v193
	v_and_b32_e32 v10, 24, v0
	s_and_b32 s22, s13, 0x60
	v_lshl_add_u64 v[0:1], v[2:3], 0, s[76:77]
	s_mov_b32 m0, s36
	s_add_i32 s37, s36, 0x2000
	s_add_i32 s38, s29, 0x8000
	s_add_i32 s39, s29, 0xa000
	v_lshl_add_u64 v[6:7], s[6:7], 0, v[134:135]
	v_mov_b32_e32 v133, v193
	global_load_lds_dwordx4 v[0:1], off
	v_lshl_add_u64 v[0:1], v[4:5], 0, s[76:77]
	s_mov_b32 m0, s37
	s_add_u32 s14, s8, 0x40080
	v_lshl_add_u64 v[8:9], s[6:7], 0, v[132:133]
	global_load_lds_dwordx4 v[0:1], off
	v_lshl_add_u64 v[0:1], v[6:7], 0, s[76:77]
	s_mov_b32 m0, s38
	s_addc_u32 s15, s9, 0
	s_add_i32 s40, s16, 0x1c000
	global_load_lds_dwordx4 v[0:1], off
	v_lshl_add_u64 v[0:1], v[8:9], 0, s[76:77]
	s_mov_b32 m0, s39
	s_add_i32 s41, s40, s2
	global_load_lds_dwordx4 v[0:1], off
	v_lshl_add_u64 v[0:1], s[14:15], 0, v[192:193]
	s_mov_b32 m0, s41
	s_add_i32 s42, s41, 0x2000
	global_load_lds_dwordx4 v[0:1], off
	v_lshl_add_u64 v[0:1], s[14:15], 0, v[130:131]
	s_mov_b32 m0, s42
	v_lshl_or_b32 v129, s10, 6, v26
	global_load_lds_dwordx4 v[0:1], off
	s_waitcnt vmcnt(8)
	s_barrier
	s_waitcnt vmcnt(6)
	v_mov_b32_e32 v127, 0
	s_cmp_lt_i32 s17, 64
	v_lshlrev_b32_e32 v128, 1, v10
	v_mov_b32_e32 v126, 0
	v_mov_b32_e32 v125, 0
	v_mov_b32_e32 v124, 0
	v_mov_b32_e32 v123, 0
	v_mov_b32_e32 v122, 0
	v_mov_b32_e32 v121, 0
	v_mov_b32_e32 v120, 0
	v_mov_b32_e32 v101, 0
	v_mov_b32_e32 v100, 0
	v_mov_b32_e32 v103, 0
	v_mov_b32_e32 v102, 0
	v_mov_b32_e32 v109, 0
	v_mov_b32_e32 v108, 0
	v_mov_b32_e32 v111, 0
	v_mov_b32_e32 v110, 0
	v_mov_b32_e32 v85, 0
	v_mov_b32_e32 v84, 0
	v_mov_b32_e32 v87, 0
	v_mov_b32_e32 v86, 0
	v_mov_b32_e32 v93, 0
	v_mov_b32_e32 v92, 0
	v_mov_b32_e32 v95, 0
	v_mov_b32_e32 v94, 0
	v_mov_b32_e32 v73, 0
	v_mov_b32_e32 v72, 0
	v_mov_b32_e32 v75, 0
	v_mov_b32_e32 v74, 0
	v_mov_b32_e32 v77, 0
	v_mov_b32_e32 v76, 0
	v_mov_b32_e32 v79, 0
	v_mov_b32_e32 v78, 0
	v_mov_b32_e32 v137, 0
	v_mov_b32_e32 v136, 0
	v_mov_b32_e32 v139, 0
	v_mov_b32_e32 v138, 0
	v_mov_b32_e32 v141, 0
	v_mov_b32_e32 v140, 0
	v_mov_b32_e32 v143, 0
	v_mov_b32_e32 v142, 0
	v_mov_b32_e32 v113, 0
	v_mov_b32_e32 v112, 0
	v_mov_b32_e32 v115, 0
	v_mov_b32_e32 v114, 0
	v_mov_b32_e32 v117, 0
	v_mov_b32_e32 v116, 0
	v_mov_b32_e32 v119, 0
	v_mov_b32_e32 v118, 0
	v_mov_b32_e32 v97, 0
	v_mov_b32_e32 v96, 0
	v_mov_b32_e32 v99, 0
	v_mov_b32_e32 v98, 0
	v_mov_b32_e32 v105, 0
	v_mov_b32_e32 v104, 0
	v_mov_b32_e32 v107, 0
	v_mov_b32_e32 v106, 0
	v_mov_b32_e32 v71, 0
	v_mov_b32_e32 v70, 0
	v_mov_b32_e32 v69, 0
	v_mov_b32_e32 v68, 0
	v_mov_b32_e32 v67, 0
	v_mov_b32_e32 v66, 0
	v_mov_b32_e32 v65, 0
	v_mov_b32_e32 v64, 0
	v_mov_b32_e32 v63, 0
	v_mov_b32_e32 v62, 0
	v_mov_b32_e32 v61, 0
	v_mov_b32_e32 v60, 0
	v_mov_b32_e32 v59, 0
	v_mov_b32_e32 v58, 0
	v_mov_b32_e32 v57, 0
	v_mov_b32_e32 v56, 0
	v_mov_b32_e32 v37, 0
	v_mov_b32_e32 v36, 0
	v_mov_b32_e32 v39, 0
	v_mov_b32_e32 v38, 0
	v_mov_b32_e32 v45, 0
	v_mov_b32_e32 v44, 0
	v_mov_b32_e32 v47, 0
	v_mov_b32_e32 v46, 0
	v_mov_b32_e32 v21, 0
	v_mov_b32_e32 v20, 0
	v_mov_b32_e32 v23, 0
	v_mov_b32_e32 v22, 0
	v_mov_b32_e32 v29, 0
	v_mov_b32_e32 v28, 0
	v_mov_b32_e32 v31, 0
	v_mov_b32_e32 v30, 0
	v_mov_b32_e32 v9, 0
	v_mov_b32_e32 v8, 0
	v_mov_b32_e32 v11, 0
	v_mov_b32_e32 v10, 0
	v_mov_b32_e32 v13, 0
	v_mov_b32_e32 v12, 0
	v_mov_b32_e32 v15, 0
	v_mov_b32_e32 v14, 0
	v_mov_b32_e32 v81, 0
	v_mov_b32_e32 v80, 0
	v_mov_b32_e32 v83, 0
	v_mov_b32_e32 v82, 0
	v_mov_b32_e32 v89, 0
	v_mov_b32_e32 v88, 0
	v_mov_b32_e32 v91, 0
	v_mov_b32_e32 v90, 0
	v_mov_b32_e32 v49, 0
	v_mov_b32_e32 v48, 0
	v_mov_b32_e32 v51, 0
	v_mov_b32_e32 v50, 0
	v_mov_b32_e32 v53, 0
	v_mov_b32_e32 v52, 0
	v_mov_b32_e32 v55, 0
	v_mov_b32_e32 v54, 0
	v_mov_b32_e32 v33, 0
	v_mov_b32_e32 v32, 0
	v_mov_b32_e32 v35, 0
	v_mov_b32_e32 v34, 0
	v_mov_b32_e32 v41, 0
	v_mov_b32_e32 v40, 0
	v_mov_b32_e32 v43, 0
	v_mov_b32_e32 v42, 0
	v_mov_b32_e32 v7, 0
	v_mov_b32_e32 v6, 0
	v_mov_b32_e32 v5, 0
	v_mov_b32_e32 v4, 0
	v_mov_b32_e32 v3, 0
	v_mov_b32_e32 v2, 0
	v_mov_b32_e32 v1, 0
	v_mov_b32_e32 v0, 0
	s_barrier
;     __device__ __forceinline__ size_t aoff(const Unit& u, size_t tstep) const { return (size_t)u.pm * tstep; }
;     __device__ __forceinline__ size_t boff(const Unit& u, size_t tstep) const { return (size_t)u.pn * tstep; }
; template <class Epi, class Sched, bool ALIGN_EPI = false, bool SP2 = false>
; __device__ __forceinline__ void gemm_phase(PG8_LAS unsigned char* lds, const Gemm g, const Sched& S, const Epi& E) {
;     ...
;     for (int i = 0; i < 2; ++i) { int R, C; stage_rc(tid * 16 + i * 8192, R, C); const int Rb = Epi::PERM ? ((R & ~31) + perm32(R & 31)) : R;
;         voffA[i] = (unsigned)(R * g.lda + C) * 2u; voffB[i] = (unsigned)(Rb * g.ldb + C) * 2u; }
;     const size_t kstep = (size_t)(BK * 2);
;     const size_t hstepA = (size_t)HALF * g.lda * 2, hstepB = (size_t)HALF * g.ldb * 2;
;     const size_t tstepA = 2 * hstepA, tstepB = 2 * hstepB;
;     const unsigned ldsw = (unsigned)wid * 1024u;
;     const int aoff = lds_byte(wr * 64 + fr, fq * 8), boff = lds_byte(wc * 32 + fr, fq * 8);
;     ...
;     f32x4 acc[2][2][4][2];
; #pragma unroll
;     for (int a = 0; a < 2; ++a)
; #pragma unroll
;         for (int b = 0; b < 2; ++b)
; #pragma unroll
;             for (int m = 0; m < 4; ++m)
; #pragma unroll
;                 for (int n = 0; n < 2; ++n) acc[a][b][m][n] = (f32x4){0.f, 0.f, 0.f, 0.f};
	s_cbranch_scc1 .LBB0_433
	v_lshlrev_b32_e32 v0, 6, v129
	s_movk_i32 s2, 0x3c0
	v_lshlrev_b32_e32 v1, 2, v129
	v_and_or_b32 v0, v0, s2, v128
	s_lshl_b32 s2, s10, 13
	v_and_b32_e32 v1, 32, v1
	v_bitop3_b32 v2, v0, s2, v1 bitop3:0xde
	v_lshlrev_b32_e32 v1, 2, v26
	v_lshl_or_b32 v0, v26, 6, v128
	s_lshl_b32 s2, s22, 7
	v_and_b32_e32 v1, 32, v1
	v_bitop3_b32 v140, v0, s2, v1 bitop3:0xde
	v_lshlrev_b32_e32 v0, 15, v16
	s_lshl_b32 s2, s12, 1
	s_lshl_b32 s10, s11, 1
	v_and_b32_e32 v0, 0xffff0000, v0
	s_and_b32 s2, s2, 0x100000
	s_and_b32 s10, s10, 0x600
	s_add_i32 s43, s1, -2
	v_lshl_add_u32 v0, v17, 12, v0
	v_and_b32_e32 v1, 1, v16
	s_or_b32 s2, s2, s10
	v_lshl_or_b32 v0, v1, 6, v0
	s_add_u32 s10, s4, s2
	v_lshl_add_u32 v0, v18, 1, v0
	v_mov_b32_e32 v1, v193
	s_addc_u32 s11, s5, 0
	v_lshl_add_u64 v[136:137], s[10:11], 0, v[0:1]
	v_lshlrev_b32_e32 v0, 15, v19
	v_and_b32_e32 v0, 0xffff0000, v0
	v_lshl_add_u32 v0, v24, 12, v0
	v_and_b32_e32 v1, 1, v19
	v_lshl_or_b32 v0, v1, 6, v0
	v_lshl_add_u32 v0, v25, 1, v0
	v_mov_b32_e32 v1, v193
	v_lshl_add_u64 v[138:139], s[10:11], 0, v[0:1]
	v_mov_b32_e32 v0, 0
	s_mov_b32 s12, 0
	s_mov_b64 s[10:11], 0x3480080
	v_add_u32_e32 v141, s16, v2
	v_mov_b32_e32 v1, v0
	v_mov_b32_e32 v2, v0
	v_mov_b32_e32 v3, v0
	v_mov_b32_e32 v4, v0
	v_mov_b32_e32 v5, v0
	v_mov_b32_e32 v6, v0
	v_mov_b32_e32 v7, v0
	v_mov_b32_e32 v8, v0
	v_mov_b32_e32 v9, v0
	v_mov_b32_e32 v10, v0
	v_mov_b32_e32 v11, v0
	v_mov_b32_e32 v12, v0
	v_mov_b32_e32 v13, v0
	v_mov_b32_e32 v14, v0
	v_mov_b32_e32 v15, v0
	v_mov_b32_e32 v20, v0
	v_mov_b32_e32 v21, v0
	v_mov_b32_e32 v22, v0
	v_mov_b32_e32 v23, v0
	v_mov_b32_e32 v28, v0
	v_mov_b32_e32 v29, v0
	v_mov_b32_e32 v30, v0
	v_mov_b32_e32 v31, v0
	v_mov_b32_e32 v36, v0
	v_mov_b32_e32 v37, v0
	v_mov_b32_e32 v38, v0
	v_mov_b32_e32 v39, v0
	v_mov_b32_e32 v44, v0
	v_mov_b32_e32 v45, v0
	v_mov_b32_e32 v46, v0
	v_mov_b32_e32 v47, v0
	v_mov_b32_e32 v16, v0
	v_mov_b32_e32 v17, v0
	v_mov_b32_e32 v18, v0
	v_mov_b32_e32 v19, v0
	v_mov_b32_e32 v24, v0
	v_mov_b32_e32 v25, v0
	v_mov_b32_e32 v26, v0
	v_mov_b32_e32 v27, v0
	v_mov_b32_e32 v32, v0
	v_mov_b32_e32 v33, v0
	v_mov_b32_e32 v34, v0
	v_mov_b32_e32 v35, v0
	v_mov_b32_e32 v40, v0
	v_mov_b32_e32 v41, v0
	v_mov_b32_e32 v42, v0
	v_mov_b32_e32 v43, v0
	v_mov_b32_e32 v48, v0
	v_mov_b32_e32 v49, v0
	v_mov_b32_e32 v50, v0
	v_mov_b32_e32 v51, v0
	v_mov_b32_e32 v52, v0
	v_mov_b32_e32 v53, v0
	v_mov_b32_e32 v54, v0
	v_mov_b32_e32 v55, v0
	v_mov_b32_e32 v56, v0
	v_mov_b32_e32 v57, v0
	v_mov_b32_e32 v58, v0
	v_mov_b32_e32 v59, v0
	v_mov_b32_e32 v60, v0
	v_mov_b32_e32 v61, v0
	v_mov_b32_e32 v62, v0
	v_mov_b32_e32 v63, v0
	v_mov_b32_e32 v64, v0
	v_mov_b32_e32 v65, v0
	v_mov_b32_e32 v66, v0
	v_mov_b32_e32 v67, v0
	v_mov_b32_e32 v68, v0
	v_mov_b32_e32 v69, v0
	v_mov_b32_e32 v70, v0
	v_mov_b32_e32 v71, v0
	v_mov_b32_e32 v72, v0
	v_mov_b32_e32 v73, v0
	v_mov_b32_e32 v74, v0
	v_mov_b32_e32 v75, v0
	v_mov_b32_e32 v76, v0
	v_mov_b32_e32 v77, v0
	v_mov_b32_e32 v78, v0
	v_mov_b32_e32 v79, v0
	v_mov_b32_e32 v84, v0
	v_mov_b32_e32 v85, v0
	v_mov_b32_e32 v86, v0
	v_mov_b32_e32 v87, v0
	v_mov_b32_e32 v92, v0
	v_mov_b32_e32 v93, v0
	v_mov_b32_e32 v94, v0
	v_mov_b32_e32 v95, v0
	v_mov_b32_e32 v100, v0
	v_mov_b32_e32 v101, v0
	v_mov_b32_e32 v102, v0
	v_mov_b32_e32 v103, v0
	v_mov_b32_e32 v108, v0
	v_mov_b32_e32 v109, v0
	v_mov_b32_e32 v110, v0
	v_mov_b32_e32 v111, v0
	v_mov_b32_e32 v80, v0
	v_mov_b32_e32 v81, v0
	v_mov_b32_e32 v82, v0
	v_mov_b32_e32 v83, v0
	v_mov_b32_e32 v88, v0
	v_mov_b32_e32 v89, v0
	v_mov_b32_e32 v90, v0
	v_mov_b32_e32 v91, v0
	v_mov_b32_e32 v96, v0
	v_mov_b32_e32 v97, v0
	v_mov_b32_e32 v98, v0
	v_mov_b32_e32 v99, v0
	v_mov_b32_e32 v104, v0
	v_mov_b32_e32 v105, v0
	v_mov_b32_e32 v106, v0
	v_mov_b32_e32 v107, v0
	v_mov_b32_e32 v112, v0
	v_mov_b32_e32 v113, v0
	v_mov_b32_e32 v114, v0
	v_mov_b32_e32 v115, v0
	v_mov_b32_e32 v116, v0
	v_mov_b32_e32 v117, v0
	v_mov_b32_e32 v118, v0
	v_mov_b32_e32 v119, v0
	v_mov_b32_e32 v120, v0
	v_mov_b32_e32 v121, v0
	v_mov_b32_e32 v122, v0
	v_mov_b32_e32 v123, v0
	v_mov_b32_e32 v124, v0
	v_mov_b32_e32 v125, v0
	v_mov_b32_e32 v126, v0
	v_mov_b32_e32 v127, v0

; #define PG8_STAGE(bufoff, gbase, voff) do { _Pragma("unroll") for (int _i = 0; _i < 2; ++_i) \
;         __builtin_amdgcn_global_load_lds((const unsigned*)((const char*)(gbase) + (voff)[_i]), (PG8_LAS unsigned*)(lds + (bufoff) + ldsw + _i * 8192), 16, 0, 0); } while (0)
; #define PG8_WAIT_V(n) asm volatile("s_waitcnt vmcnt(" #n ")" ::: "memory")
; #define PG8_BAR __builtin_amdgcn_s_barrier()
; template <class Epi, class Sched, bool ALIGN_EPI = false, bool SP2 = false>
; __device__ __forceinline__ void gemm_phase(PG8_LAS unsigned char* lds, const Gemm g, const Sched& S, const Epi& E) {
;     ...
;     f32x4 acc[2][2][4][2];
; #pragma unroll
;     for (int a = 0; a < 2; ++a)
; #pragma unroll
;         for (int b = 0; b < 2; ++b)
; #pragma unroll
;             for (int m = 0; m < 4; ++m)
; #pragma unroll
;                 for (int n = 0; n < 2; ++n) acc[a][b][m][n] = (f32x4){0.f, 0.f, 0.f, 0.f};
;     ...
;         PG8_STAGE(PG8_SB(0, 0), cB, voffB); PG8_STAGE(PG8_SB(0, 1), cB + hstepB, voffB); PG8_STAGE(PG8_SA(0, 0), cA, voffA); PG8_STAGE(PG8_SA(0, 1), cA + hstepA, voffA);
;         if (wr == 1) PG8_BAR;
;         PG8_WAIT_V(2); PG8_BAR;
;         PG8_STAGE(PG8_SB(1, 0), cB + kstep, voffB); PG8_STAGE(PG8_SA(1, 0), cA + kstep, voffA); PG8_STAGE(PG8_SB(1, 1), cB + hstepB + kstep, voffB);
;         PG8_WAIT_V(6); PG8_BAR;
.LBB0_439:
	s_add_i32 s31, s16, 0x18000
	s_lshl_b32 s13, s13, 5
	s_add_i32 s34, s31, s2
	s_and_b32 s18, s13, 0x60
	v_lshl_add_u64 v[0:1], v[0:1], 0, s[90:91]
	s_mov_b32 m0, s34
	s_add_i32 s35, s34, 0x2000
	s_add_i32 s36, s27, 0x8000
	s_add_i32 s37, s27, 0xa000
	v_lshl_add_u64 v[6:7], s[6:7], 0, v[192:193]
	v_mov_b32_e32 v133, v193
	global_load_lds_dwordx4 v[0:1], off
	v_lshl_add_u64 v[0:1], v[2:3], 0, s[90:91]
	s_mov_b32 m0, s35
	s_add_u32 s14, s8, 0x80880
	v_lshl_add_u64 v[8:9], s[6:7], 0, v[132:133]
	global_load_lds_dwordx4 v[0:1], off
	v_lshl_add_u64 v[0:1], v[6:7], 0, s[76:77]
	s_mov_b32 m0, s36
	s_addc_u32 s15, s9, 0
	s_add_i32 s38, s16, 0x1c000
	global_load_lds_dwordx4 v[0:1], off
	v_lshl_add_u64 v[0:1], v[8:9], 0, s[76:77]
	s_mov_b32 m0, s37
	s_add_i32 s39, s38, s2
	global_load_lds_dwordx4 v[0:1], off
	v_lshl_add_u64 v[0:1], s[14:15], 0, v[134:135]
	s_mov_b32 m0, s39
	s_add_i32 s40, s39, 0x2000
	global_load_lds_dwordx4 v[0:1], off
	v_lshl_add_u64 v[0:1], s[14:15], 0, v[130:131]
	s_mov_b32 m0, s40
	v_and_b32_e32 v140, 15, v4
	global_load_lds_dwordx4 v[0:1], off
	s_waitcnt vmcnt(8)
	s_barrier
	v_lshrrev_b32_e32 v4, 1, v4
	s_waitcnt vmcnt(6)
	v_and_b32_e32 v4, 24, v4
	v_mov_b32_e32 v123, 0
	v_lshl_or_b32 v129, s10, 6, v140
	s_cmp_lt_i32 s17, 64
	v_lshlrev_b32_e32 v128, 1, v4
	v_mov_b32_e32 v122, v123
	v_mov_b32_e32 v121, v123
	v_mov_b32_e32 v120, v123
	v_mov_b32_e32 v127, v123
	v_mov_b32_e32 v126, v123
	v_mov_b32_e32 v125, v123
	v_mov_b32_e32 v124, v123
	v_mov_b32_e32 v111, v123
	v_mov_b32_e32 v110, v123
	v_mov_b32_e32 v109, v123
	v_mov_b32_e32 v108, v123
	v_mov_b32_e32 v107, v123
	v_mov_b32_e32 v106, v123
	v_mov_b32_e32 v105, v123
	v_mov_b32_e32 v104, v123
	v_mov_b32_e32 v95, v123
	v_mov_b32_e32 v94, v123
	v_mov_b32_e32 v93, v123
	v_mov_b32_e32 v92, v123
	v_mov_b32_e32 v91, v123
	v_mov_b32_e32 v90, v123
	v_mov_b32_e32 v89, v123
	v_mov_b32_e32 v88, v123
	v_mov_b32_e32 v79, v123
	v_mov_b32_e32 v78, v123
	v_mov_b32_e32 v77, v123
	v_mov_b32_e32 v76, v123
	v_mov_b32_e32 v75, v123
	v_mov_b32_e32 v74, v123
	v_mov_b32_e32 v73, v123
	v_mov_b32_e32 v72, v123
	v_mov_b32_e32 v119, v123
	v_mov_b32_e32 v118, v123
	v_mov_b32_e32 v117, v123
	v_mov_b32_e32 v116, v123
	v_mov_b32_e32 v115, v123
	v_mov_b32_e32 v114, v123
	v_mov_b32_e32 v113, v123
	v_mov_b32_e32 v112, v123
	v_mov_b32_e32 v103, v123
	v_mov_b32_e32 v102, v123
	v_mov_b32_e32 v101, v123
	v_mov_b32_e32 v100, v123
	v_mov_b32_e32 v99, v123
	v_mov_b32_e32 v98, v123
	v_mov_b32_e32 v97, v123
	v_mov_b32_e32 v96, v123
	v_mov_b32_e32 v87, v123
	v_mov_b32_e32 v86, v123
	v_mov_b32_e32 v85, v123
	v_mov_b32_e32 v84, v123
	v_mov_b32_e32 v83, v123
	v_mov_b32_e32 v82, v123
	v_mov_b32_e32 v81, v123
	v_mov_b32_e32 v80, v123
	v_mov_b32_e32 v71, v123
	v_mov_b32_e32 v70, v123
	v_mov_b32_e32 v69, v123
	v_mov_b32_e32 v68, v123
	v_mov_b32_e32 v67, v123
	v_mov_b32_e32 v66, v123
	v_mov_b32_e32 v65, v123
	v_mov_b32_e32 v64, v123
	v_mov_b32_e32 v63, v123
	v_mov_b32_e32 v62, v123
	v_mov_b32_e32 v61, v123
	v_mov_b32_e32 v60, v123
	v_mov_b32_e32 v59, v123
	v_mov_b32_e32 v58, v123
	v_mov_b32_e32 v57, v123
	v_mov_b32_e32 v56, v123
	v_mov_b32_e32 v47, v123
	v_mov_b32_e32 v46, v123
	v_mov_b32_e32 v45, v123
	v_mov_b32_e32 v44, v123
	v_mov_b32_e32 v43, v123
	v_mov_b32_e32 v42, v123
	v_mov_b32_e32 v41, v123
	v_mov_b32_e32 v40, v123
	v_mov_b32_e32 v31, v123
	v_mov_b32_e32 v30, v123
	v_mov_b32_e32 v29, v123
	v_mov_b32_e32 v28, v123
	v_mov_b32_e32 v27, v123
	v_mov_b32_e32 v26, v123
	v_mov_b32_e32 v25, v123
	v_mov_b32_e32 v24, v123
	v_mov_b32_e32 v15, v123
	v_mov_b32_e32 v14, v123
	v_mov_b32_e32 v13, v123
	v_mov_b32_e32 v12, v123
	v_mov_b32_e32 v11, v123
	v_mov_b32_e32 v10, v123
	v_mov_b32_e32 v9, v123
	v_mov_b32_e32 v8, v123
	v_mov_b32_e32 v55, v123
	v_mov_b32_e32 v54, v123
	v_mov_b32_e32 v53, v123
	v_mov_b32_e32 v52, v123
	v_mov_b32_e32 v51, v123
	v_mov_b32_e32 v50, v123
	v_mov_b32_e32 v49, v123
	v_mov_b32_e32 v48, v123
	v_mov_b32_e32 v39, v123
	v_mov_b32_e32 v38, v123
	v_mov_b32_e32 v37, v123
	v_mov_b32_e32 v36, v123
	v_mov_b32_e32 v35, v123
	v_mov_b32_e32 v34, v123
	v_mov_b32_e32 v33, v123
	v_mov_b32_e32 v32, v123
	v_mov_b32_e32 v23, v123
	v_mov_b32_e32 v22, v123
	v_mov_b32_e32 v21, v123
	v_mov_b32_e32 v20, v123
	v_mov_b32_e32 v19, v123
	v_mov_b32_e32 v18, v123
	v_mov_b32_e32 v17, v123
	v_mov_b32_e32 v16, v123
	v_mov_b32_e32 v7, v123
	v_mov_b32_e32 v6, v123
	v_mov_b32_e32 v5, v123
	v_mov_b32_e32 v4, v123
	v_mov_b32_e32 v3, v123
	v_mov_b32_e32 v2, v123
	v_mov_b32_e32 v1, v123
	v_mov_b32_e32 v0, v123
	s_barrier
;     __device__ __forceinline__ size_t aoff(const Unit& u, size_t tstep) const { return (size_t)u.pm * tstep; }
;     __device__ __forceinline__ size_t boff(const Unit& u, size_t tstep) const { return (size_t)u.pn * tstep; }
; template <class Epi, class Sched, bool ALIGN_EPI = false, bool SP2 = false>
; __device__ __forceinline__ void gemm_phase(PG8_LAS unsigned char* lds, const Gemm g, const Sched& S, const Epi& E) {
;     ...
;     for (int i = 0; i < 2; ++i) { int R, C; stage_rc(tid * 16 + i * 8192, R, C); const int Rb = Epi::PERM ? ((R & ~31) + perm32(R & 31)) : R;
;         voffA[i] = (unsigned)(R * g.lda + C) * 2u; voffB[i] = (unsigned)(Rb * g.ldb + C) * 2u; }
;     const size_t kstep = (size_t)(BK * 2);
;     const size_t hstepA = (size_t)HALF * g.lda * 2, hstepB = (size_t)HALF * g.ldb * 2;
;     const size_t tstepA = 2 * hstepA, tstepB = 2 * hstepB;
;     const unsigned ldsw = (unsigned)wid * 1024u;
;     const int aoff = lds_byte(wr * 64 + fr, fq * 8), boff = lds_byte(wc * 32 + fr, fq * 8);
;     ...
;     f32x4 acc[2][2][4][2];
; #pragma unroll
;     for (int a = 0; a < 2; ++a)
; #pragma unroll
;         for (int b = 0; b < 2; ++b)
; #pragma unroll
;             for (int m = 0; m < 4; ++m)
; #pragma unroll
;                 for (int n = 0; n < 2; ++n) acc[a][b][m][n] = (f32x4){0.f, 0.f, 0.f, 0.f};
	s_cbranch_scc1 .LBB0_442
	v_lshlrev_b32_e32 v0, 6, v129
	s_movk_i32 s2, 0x3c0
	v_lshlrev_b32_e32 v1, 2, v129
	v_and_or_b32 v0, v0, s2, v128
	s_lshl_b32 s2, s10, 13
	v_and_b32_e32 v1, 32, v1
	v_bitop3_b32 v2, v0, s2, v1 bitop3:0xde
	v_lshlrev_b32_e32 v1, 2, v140
	v_lshl_or_b32 v0, v140, 6, v128
	s_lshl_b32 s2, s18, 7
	v_and_b32_e32 v1, 32, v1
	v_bitop3_b32 v140, v0, s2, v1 bitop3:0xde
	v_lshlrev_b32_e32 v0, 14, v136
	s_lshl_b32 s2, s12, 1
	s_lshl_b32 s10, s11, 1
	v_and_b32_e32 v0, 0xffff8000, v0
	s_and_b32 s2, s2, 0x180000
	s_and_b32 s10, s10, 0x600
	s_add_i32 s17, s1, -2
	v_lshl_add_u32 v0, v137, 11, v0
	v_and_b32_e32 v1, 1, v136
	s_or_b32 s2, s2, s10
	v_lshl_or_b32 v0, v1, 6, v0
	s_add_u32 s10, s4, s2
	v_lshl_add_u32 v0, v138, 1, v0
	v_mov_b32_e32 v1, v193
	s_addc_u32 s11, s5, 0
	v_lshl_add_u64 v[136:137], s[10:11], 0, v[0:1]
	v_lshlrev_b32_e32 v0, 14, v139
	v_and_b32_e32 v0, 0xffff8000, v0
	v_lshl_add_u32 v0, v141, 11, v0
	v_and_b32_e32 v1, 1, v139
	v_lshl_or_b32 v0, v1, 6, v0
	v_lshl_add_u32 v0, v142, 1, v0
	v_mov_b32_e32 v1, v193
	v_lshl_add_u64 v[138:139], s[10:11], 0, v[0:1]
	v_mov_b32_e32 v0, 0
	s_mov_b32 s12, 0
	s_mov_b64 s[10:11], 0x2040080
	v_add_u32_e32 v141, s16, v2
	v_mov_b32_e32 v1, v0
	v_mov_b32_e32 v2, v0
	v_mov_b32_e32 v3, v0
	v_mov_b32_e32 v4, v0
	v_mov_b32_e32 v5, v0
	v_mov_b32_e32 v6, v0
	v_mov_b32_e32 v7, v0
	v_mov_b32_e32 v16, v0
	v_mov_b32_e32 v17, v0
	v_mov_b32_e32 v18, v0
	v_mov_b32_e32 v19, v0
	v_mov_b32_e32 v20, v0
	v_mov_b32_e32 v21, v0
	v_mov_b32_e32 v22, v0
	v_mov_b32_e32 v23, v0
	v_mov_b32_e32 v32, v0
	v_mov_b32_e32 v33, v0
	v_mov_b32_e32 v34, v0
	v_mov_b32_e32 v35, v0
	v_mov_b32_e32 v36, v0
	v_mov_b32_e32 v37, v0
	v_mov_b32_e32 v38, v0
	v_mov_b32_e32 v39, v0
	v_mov_b32_e32 v48, v0
	v_mov_b32_e32 v49, v0
	v_mov_b32_e32 v50, v0
	v_mov_b32_e32 v51, v0
	v_mov_b32_e32 v52, v0
	v_mov_b32_e32 v53, v0
	v_mov_b32_e32 v54, v0
	v_mov_b32_e32 v55, v0
	v_mov_b32_e32 v8, v0
	v_mov_b32_e32 v9, v0
	v_mov_b32_e32 v10, v0
	v_mov_b32_e32 v11, v0
	v_mov_b32_e32 v12, v0
	v_mov_b32_e32 v13, v0
	v_mov_b32_e32 v14, v0
	v_mov_b32_e32 v15, v0
	v_mov_b32_e32 v24, v0
	v_mov_b32_e32 v25, v0
	v_mov_b32_e32 v26, v0
	v_mov_b32_e32 v27, v0
	v_mov_b32_e32 v28, v0
	v_mov_b32_e32 v29, v0
	v_mov_b32_e32 v30, v0
	v_mov_b32_e32 v31, v0
	v_mov_b32_e32 v40, v0
	v_mov_b32_e32 v41, v0
	v_mov_b32_e32 v42, v0
	v_mov_b32_e32 v43, v0
	v_mov_b32_e32 v44, v0
	v_mov_b32_e32 v45, v0
	v_mov_b32_e32 v46, v0
	v_mov_b32_e32 v47, v0
	v_mov_b32_e32 v56, v0
	v_mov_b32_e32 v57, v0
	v_mov_b32_e32 v58, v0
	v_mov_b32_e32 v59, v0
	v_mov_b32_e32 v60, v0
	v_mov_b32_e32 v61, v0
	v_mov_b32_e32 v62, v0
	v_mov_b32_e32 v63, v0
	v_mov_b32_e32 v64, v0
	v_mov_b32_e32 v65, v0
	v_mov_b32_e32 v66, v0
	v_mov_b32_e32 v67, v0
	v_mov_b32_e32 v68, v0
	v_mov_b32_e32 v69, v0
	v_mov_b32_e32 v70, v0
	v_mov_b32_e32 v71, v0
	v_mov_b32_e32 v80, v0
	v_mov_b32_e32 v81, v0
	v_mov_b32_e32 v82, v0
	v_mov_b32_e32 v83, v0
	v_mov_b32_e32 v84, v0
	v_mov_b32_e32 v85, v0
	v_mov_b32_e32 v86, v0
	v_mov_b32_e32 v87, v0
	v_mov_b32_e32 v96, v0
	v_mov_b32_e32 v97, v0
	v_mov_b32_e32 v98, v0
	v_mov_b32_e32 v99, v0
	v_mov_b32_e32 v100, v0
	v_mov_b32_e32 v101, v0
	v_mov_b32_e32 v102, v0
	v_mov_b32_e32 v103, v0
	v_mov_b32_e32 v112, v0
	v_mov_b32_e32 v113, v0
	v_mov_b32_e32 v114, v0
	v_mov_b32_e32 v115, v0
	v_mov_b32_e32 v116, v0
	v_mov_b32_e32 v117, v0
	v_mov_b32_e32 v118, v0
	v_mov_b32_e32 v119, v0
	v_mov_b32_e32 v72, v0
	v_mov_b32_e32 v73, v0
	v_mov_b32_e32 v74, v0
	v_mov_b32_e32 v75, v0
	v_mov_b32_e32 v76, v0
	v_mov_b32_e32 v77, v0
	v_mov_b32_e32 v78, v0
	v_mov_b32_e32 v79, v0
	v_mov_b32_e32 v88, v0
	v_mov_b32_e32 v89, v0
	v_mov_b32_e32 v90, v0
	v_mov_b32_e32 v91, v0
	v_mov_b32_e32 v92, v0
	v_mov_b32_e32 v93, v0
	v_mov_b32_e32 v94, v0
	v_mov_b32_e32 v95, v0
	v_mov_b32_e32 v104, v0
	v_mov_b32_e32 v105, v0
	v_mov_b32_e32 v106, v0
	v_mov_b32_e32 v107, v0
	v_mov_b32_e32 v108, v0
	v_mov_b32_e32 v109, v0
	v_mov_b32_e32 v110, v0
	v_mov_b32_e32 v111, v0
	v_mov_b32_e32 v124, v0
	v_mov_b32_e32 v125, v0
	v_mov_b32_e32 v126, v0
	v_mov_b32_e32 v127, v0
	v_mov_b32_e32 v120, v0
	v_mov_b32_e32 v121, v0
	v_mov_b32_e32 v122, v0
	v_mov_b32_e32 v123, v0

; #define PG8_STAGE(bufoff, gbase, voff) do { _Pragma("unroll") for (int _i = 0; _i < 2; ++_i) \
;         __builtin_amdgcn_global_load_lds((const unsigned*)((const char*)(gbase) + (voff)[_i]), (PG8_LAS unsigned*)(lds + (bufoff) + ldsw + _i * 8192), 16, 0, 0); } while (0)
; #define PG8_WAIT_V(n) asm volatile("s_waitcnt vmcnt(" #n ")" ::: "memory")
; #define PG8_BAR __builtin_amdgcn_s_barrier()
; template <class Epi, class Sched, bool ALIGN_EPI = false, bool SP2 = false>
; __device__ __forceinline__ void gemm_phase(PG8_LAS unsigned char* lds, const Gemm g, const Sched& S, const Epi& E) {
;     ...
;         PG8_STAGE(PG8_SB(0, 0), cB, voffB); PG8_STAGE(PG8_SB(0, 1), cB + hstepB, voffB); PG8_STAGE(PG8_SA(0, 0), cA, voffA); PG8_STAGE(PG8_SA(0, 1), cA + hstepA, voffA);
;         if (wr == 1) PG8_BAR;
;         PG8_WAIT_V(2); PG8_BAR;
;         PG8_STAGE(PG8_SB(1, 0), cB + kstep, voffB); PG8_STAGE(PG8_SA(1, 0), cA + kstep, voffA); PG8_STAGE(PG8_SB(1, 1), cB + hstepB + kstep, voffB);
;         PG8_WAIT_V(6); PG8_BAR;
; __global__ void __launch_bounds__(NTHREADS, 2) mega_fwd(Args args) {
;     ...
;             pg8::Gemm g{(const bf16*)(ws + WS_QO), (const bf16*)(ws + WS_WOUT), M, DM, DM, DM, DM}; pg8::StaticOrder S; S.init(M, DM, G_, bx_);
;             EpiRes E{XB, SSQ, 1.0f};
;             pg8::gemm_phase<EpiRes, pg8::StaticOrder, true, true>(ldsp, g, S, E);
.LBB0_875:
	s_add_u32 s12, s4, 0x3a00000
	s_addc_u32 s13, s5, 0
	s_add_u32 s14, s4, 0x3600000
	v_bfe_u32 v15, v11, 4, 2
	s_addc_u32 s15, s5, 0
	v_and_b32_e32 v16, 15, v11
	v_lshlrev_b32_e32 v18, 4, v15
	v_lshlrev_b32_e32 v11, 2, v11
	s_add_i32 s60, s18, 0x18000
	s_and_b32 s51, s6, 3
	v_lshl_or_b32 v144, s7, 6, v16
	v_lshl_or_b32 v16, v16, 6, v18
	s_lshl_b32 s4, s7, 13
	v_and_b32_e32 v11, 32, v11
	s_add_i32 s61, s60, s2
	v_bitop3_b32 v18, v16, s4, v11 bitop3:0xde
	s_lshl_b32 s4, s51, 12
	v_lshl_add_u64 v[6:7], v[6:7], 0, s[76:77]
	s_mov_b32 m0, s61
	s_add_i32 s64, s61, 0x2000
	s_add_i32 s65, s45, 0x8000
	s_add_i32 s66, s45, 0xa000
	v_bitop3_b32 v145, v16, s4, v11 bitop3:0xde
	global_load_lds_dwordx4 v[6:7], off
	v_lshl_add_u64 v[4:5], v[4:5], 0, s[76:77]
	s_mov_b32 m0, s64
	s_add_u32 s4, s28, 0x40080
	global_load_lds_dwordx4 v[4:5], off
	v_lshl_add_u64 v[0:1], v[0:1], 0, s[76:77]
	s_mov_b32 m0, s65
	s_addc_u32 s5, s29, 0
	s_add_i32 s67, s18, 0x1c000
	global_load_lds_dwordx4 v[0:1], off
	v_lshl_add_u64 v[0:1], v[2:3], 0, s[76:77]
	s_mov_b32 m0, s66
	s_add_i32 s70, s67, s2
	global_load_lds_dwordx4 v[0:1], off
	v_lshl_add_u64 v[0:1], s[4:5], 0, v[192:193]
	s_mov_b32 m0, s70
	s_add_i32 s71, s70, 0x2000
	global_load_lds_dwordx4 v[0:1], off
	v_lshl_add_u64 v[0:1], s[4:5], 0, v[132:133]
	s_mov_b32 m0, s71
	v_lshlrev_b32_e32 v17, 3, v15
	global_load_lds_dwordx4 v[0:1], off
	s_waitcnt vmcnt(8)
	s_barrier
	v_lshlrev_b32_e32 v0, 14, v12
	v_and_b32_e32 v0, 0xffff8000, v0
	v_lshl_add_u32 v0, v13, 11, v0
	v_and_b32_e32 v1, 1, v12
	v_lshl_or_b32 v0, v1, 6, v0
	v_lshl_add_u32 v134, v14, 1, v0
	v_lshlrev_b32_e32 v0, 14, v8
	v_and_b32_e32 v0, 0xffff8000, v0
	s_waitcnt vmcnt(6)
	v_lshl_add_u32 v0, v9, 11, v0
	v_and_b32_e32 v1, 1, v8
	s_cmpk_lt_u32 s16, 0x100
	v_lshl_or_b32 v0, v1, 6, v0
	v_lshl_or_b32 v146, s51, 5, v17
	s_cselect_b64 s[16:17], -1, 0
	s_mov_b32 s72, 0
	v_cmp_eq_u32_e64 s[4:5], 0, v15
	s_ashr_i32 s74, s1, 31
	s_ashr_i32 s75, s0, 31
	v_mov_b32_e32 v135, v193
	v_lshl_add_u32 v136, v10, 1, v0
	v_mov_b32_e32 v137, v193
	v_add_u32_e32 v147, s18, v18
	s_barrier
	s_branch .LBB0_878

; #define PG8_STAGE(bufoff, gbase, voff) do { _Pragma("unroll") for (int _i = 0; _i < 2; ++_i) \
;         __builtin_amdgcn_global_load_lds((const unsigned*)((const char*)(gbase) + (voff)[_i]), (PG8_LAS unsigned*)(lds + (bufoff) + ldsw + _i * 8192), 16, 0, 0); } while (0)
; #define PG8_WAIT_V(n) asm volatile("s_waitcnt vmcnt(" #n ")" ::: "memory")
; #define PG8_BAR __builtin_amdgcn_s_barrier()
; #define LAS __attribute__((address_space(3)))
; template <class Epi, class Sched, bool ALIGN_EPI = false, bool SP2 = false>
; __device__ __forceinline__ void gemm_phase(PG8_LAS unsigned char* lds, const Gemm g, const Sched& S, const Epi& E) {
;     ...
;         PG8_STAGE(PG8_SB(0, 0), cB, voffB); PG8_STAGE(PG8_SB(0, 1), cB + hstepB, voffB); PG8_STAGE(PG8_SA(0, 0), cA, voffA); PG8_STAGE(PG8_SA(0, 1), cA + hstepA, voffA);
;         if (wr == 1) PG8_BAR;
;         PG8_WAIT_V(2); PG8_BAR;
;         PG8_STAGE(PG8_SB(1, 0), cB + kstep, voffB); PG8_STAGE(PG8_SA(1, 0), cA + kstep, voffA); PG8_STAGE(PG8_SB(1, 1), cB + hstepB + kstep, voffB);
;         PG8_WAIT_V(6); PG8_BAR;
; __global__ void __launch_bounds__(NTHREADS, 2) mega_fwd(Args args) {
;     ...
;             pg8::Gemm g{XB, (const bf16*)(ws + WS_WQK), M, DM, DM, DM, DM}; pg8::BatchOrder S; S.init(M, DM, G_, bx_); S.mb = SEQ / 256; S.bstride = (size_t)DM * DM * 2;
;             EpiSoftmax E{(bf16*)(ws + WS_PB), SSQ, (LAS float*)(ldsp + 131072)};
;             pg8::gemm_phase<EpiSoftmax, pg8::BatchOrder, true, true>(ldsp, g, S, E);
.LBB0_985:
	s_add_u32 s10, s6, 0x5a00000
	s_addc_u32 s11, s7, 0
	s_add_i32 s50, s14, 0x18000
	s_and_b32 s2, s2, 3
	s_add_i32 s51, s50, s5
	s_add_i32 s15, s14, 0x20000
	s_lshl_b32 s13, s4, 13
	s_lshl_b32 s18, s2, 5
	s_lshl_b32 s19, s2, 12
	v_lshl_add_u64 v[6:7], v[6:7], 0, s[76:77]
	s_mov_b32 m0, s51
	s_add_i32 s60, s51, 0x2000
	s_add_i32 s61, s44, 0x8000
	s_add_i32 s64, s44, 0xa000
	global_load_lds_dwordx4 v[6:7], off
	v_lshl_add_u64 v[4:5], v[4:5], 0, s[76:77]
	s_mov_b32 m0, s60
	s_add_u32 s16, s26, 0x40080
	global_load_lds_dwordx4 v[4:5], off
	v_lshl_add_u64 v[0:1], v[0:1], 0, s[76:77]
	s_mov_b32 m0, s61
	s_addc_u32 s17, s27, 0
	s_add_i32 s65, s14, 0x1c000
	global_load_lds_dwordx4 v[0:1], off
	v_lshl_add_u64 v[0:1], v[2:3], 0, s[76:77]
	s_mov_b32 m0, s64
	s_add_i32 s66, s65, s5
	global_load_lds_dwordx4 v[0:1], off
	v_lshl_add_u64 v[0:1], s[16:17], 0, v[130:131]
	s_mov_b32 m0, s66
	s_add_i32 s67, s66, 0x2000
	global_load_lds_dwordx4 v[0:1], off
	v_lshl_add_u64 v[0:1], s[16:17], 0, v[134:135]
	s_mov_b32 m0, s67
	v_bfe_u32 v2, v8, 4, 2
	global_load_lds_dwordx4 v[0:1], off
	s_waitcnt vmcnt(8)
	s_barrier
	v_and_b32_e32 v1, 15, v8
	v_lshlrev_b32_e32 v192, 4, v2
	v_lshlrev_b32_e32 v3, 2, v8
	v_lshl_or_b32 v174, s4, 6, v1
	v_lshl_or_b32 v1, v1, 6, v192
	v_and_b32_e32 v3, 32, v3
	v_bitop3_b32 v4, v1, s13, v3 bitop3:0xde
	v_bitop3_b32 v175, v1, s19, v3 bitop3:0xde
	v_lshlrev_b32_e32 v1, 14, v12
	v_lshlrev_b32_e32 v0, 3, v2
	v_cmp_eq_u32_e64 s[4:5], 0, v2
	v_lshl_add_u64 v[2:3], s[6:7], 0, v[192:193]
	s_mov_b64 s[6:7], 0x3600000
	v_and_b32_e32 v1, 0xffff8000, v1
	v_lshl_add_u64 v[136:137], v[2:3], 0, s[6:7]
	v_lshl_add_u32 v1, v13, 11, v1
	v_and_b32_e32 v2, 1, v12
	v_lshl_or_b32 v1, v2, 6, v1
	v_lshl_add_u32 v138, v14, 1, v1
	v_lshlrev_b32_e32 v1, 14, v9
	v_lshlrev_b32_e32 v176, 4, v174
	v_and_b32_e32 v1, 0xffff8000, v1
	s_waitcnt vmcnt(6)
	s_cmpk_lt_u32 s12, 0x100
	v_or_b32_e32 v177, 0x100, v176
	v_or_b32_e32 v254, 0x200, v176
	v_or_b32_e32 v213, 0x300, v176
	v_add_u32_e32 v180, s15, v176
	v_lshl_add_u32 v1, v10, 11, v1
	v_and_b32_e32 v2, 1, v9
	s_cselect_b64 s[12:13], -1, 0
	s_lshl_b32 s2, s2, 2
	v_add_u32_e32 v182, s15, v177
	v_add_u32_e32 v184, s15, v254
	v_add_u32_e32 v186, s15, v213
	v_add_u32_e32 v188, 0x800, v180
	v_add_u32_e32 v190, 0x900, v180
	v_add_u32_e32 v202, 0xa00, v180
	v_add_u32_e32 v205, 0xb00, v180
	v_lshl_or_b32 v1, v2, 6, v1
	s_mov_b32 s70, 0
	s_ashr_i32 s71, s1, 31
	s_ashr_i32 s72, s0, 31
	s_add_i32 s74, s15, s2
	v_add_u32_e32 v181, s2, v180
	v_add_u32_e32 v183, s2, v182
	v_add_u32_e32 v185, s2, v184
	v_add_u32_e32 v187, s2, v186
	v_add_u32_e32 v189, s2, v188
	v_add_u32_e32 v191, s2, v190
	v_add_u32_e32 v204, s2, v202
	v_add_u32_e32 v206, s2, v205
	s_add_i32 s75, s14, 0x21000
	v_mov_b32_e32 v139, v193
	v_lshl_add_u32 v140, v11, 1, v1
	v_mov_b32_e32 v141, v193
	v_add_u32_e32 v207, s14, v4
	s_lshl_b32 s68, s18, 1
	v_lshlrev_b32_e32 v192, 1, v0
	s_barrier
	s_branch .LBB0_988

; #define PG8_STAGE(bufoff, gbase, voff) do { _Pragma("unroll") for (int _i = 0; _i < 2; ++_i) \
;         __builtin_amdgcn_global_load_lds((const unsigned*)((const char*)(gbase) + (voff)[_i]), (PG8_LAS unsigned*)(lds + (bufoff) + ldsw + _i * 8192), 16, 0, 0); } while (0)
; #define PG8_WAIT_V(n) asm volatile("s_waitcnt vmcnt(" #n ")" ::: "memory")
; #define PG8_BAR __builtin_amdgcn_s_barrier()
; template <class Epi, class Sched, bool ALIGN_EPI = false, bool SP2 = false>
; __device__ __forceinline__ void gemm_phase(PG8_LAS unsigned char* lds, const Gemm g, const Sched& S, const Epi& E) {
;     ...
;         PG8_STAGE(PG8_SB(0, 0), cB, voffB); PG8_STAGE(PG8_SB(0, 1), cB + hstepB, voffB); PG8_STAGE(PG8_SA(0, 0), cA, voffA); PG8_STAGE(PG8_SA(0, 1), cA + hstepA, voffA);
;         if (wr == 1) PG8_BAR;
;         PG8_WAIT_V(2); PG8_BAR;
;         PG8_STAGE(PG8_SB(1, 0), cB + kstep, voffB); PG8_STAGE(PG8_SA(1, 0), cA + kstep, voffA); PG8_STAGE(PG8_SB(1, 1), cB + hstepB + kstep, voffB);
;         PG8_WAIT_V(6); PG8_BAR;
; __global__ void __launch_bounds__(NTHREADS, 2) mega_fwd(Args args) {
;     ...
;             pg8::Gemm g{(const bf16*)(ws + WS_PB), (const bf16*)(ws + WS_VWO), M, DM, DM, DM, DM}; pg8::BatchOrder S; S.init(M, DM, G_, bx_); S.mb = SEQ / 256; S.bstride = (size_t)DM * DM * 2;
;             EpiRes E{XB, SSQ, 1.0f};
;             pg8::gemm_phase<EpiRes, pg8::BatchOrder, true, true>(ldsp, g, S, E);
.LBB0_1111:
	s_add_u32 s12, s4, 0x3a00000
	s_addc_u32 s13, s5, 0
	s_add_u32 s14, s4, 0x3600000
	v_bfe_u32 v16, v11, 4, 2
	s_addc_u32 s15, s5, 0
	v_and_b32_e32 v15, 15, v11
	v_lshlrev_b32_e32 v18, 4, v16
	v_lshlrev_b32_e32 v11, 2, v11
	s_add_i32 s60, s18, 0x18000
	s_and_b32 s51, s6, 3
	v_lshl_or_b32 v144, s7, 6, v15
	v_lshl_or_b32 v15, v15, 6, v18
	s_lshl_b32 s4, s7, 13
	v_and_b32_e32 v11, 32, v11
	s_add_i32 s61, s60, s2
	v_bitop3_b32 v18, v15, s4, v11 bitop3:0xde
	s_lshl_b32 s4, s51, 12
	v_lshl_add_u64 v[6:7], v[6:7], 0, s[76:77]
	s_mov_b32 m0, s61
	s_add_i32 s64, s61, 0x2000
	s_add_i32 s65, s45, 0x8000
	s_add_i32 s66, s45, 0xa000
	v_bitop3_b32 v145, v15, s4, v11 bitop3:0xde
	global_load_lds_dwordx4 v[6:7], off
	v_lshl_add_u64 v[4:5], v[4:5], 0, s[76:77]
	s_mov_b32 m0, s64
	s_add_u32 s4, s28, 0x40080
	global_load_lds_dwordx4 v[4:5], off
	v_lshl_add_u64 v[0:1], v[0:1], 0, s[76:77]
	s_mov_b32 m0, s65
	s_addc_u32 s5, s29, 0
	s_add_i32 s67, s18, 0x1c000
	global_load_lds_dwordx4 v[0:1], off
	v_lshl_add_u64 v[0:1], v[2:3], 0, s[76:77]
	s_mov_b32 m0, s66
	s_add_i32 s70, s67, s2
	global_load_lds_dwordx4 v[0:1], off
	v_lshl_add_u64 v[0:1], s[4:5], 0, v[192:193]
	s_mov_b32 m0, s70
	s_add_i32 s71, s70, 0x2000
	global_load_lds_dwordx4 v[0:1], off
	v_lshl_add_u64 v[0:1], s[4:5], 0, v[132:133]
	s_mov_b32 m0, s71
	v_lshlrev_b32_e32 v17, 3, v16
	global_load_lds_dwordx4 v[0:1], off
	s_waitcnt vmcnt(8)
	s_barrier
	v_lshlrev_b32_e32 v0, 14, v12
	v_and_b32_e32 v0, 0xffff8000, v0
	v_lshl_add_u32 v0, v13, 11, v0
	v_and_b32_e32 v1, 1, v12
	v_lshl_or_b32 v0, v1, 6, v0
	v_lshl_add_u32 v134, v14, 1, v0
	v_lshlrev_b32_e32 v0, 14, v8
	v_and_b32_e32 v0, 0xffff8000, v0
	s_waitcnt vmcnt(6)
	v_lshl_add_u32 v0, v9, 11, v0
	v_and_b32_e32 v1, 1, v8
	s_cmpk_lt_u32 s16, 0x100
	v_lshl_or_b32 v0, v1, 6, v0
	v_lshl_or_b32 v146, s51, 5, v17
	s_cselect_b64 s[16:17], -1, 0
	s_mov_b32 s72, 0
	v_cmp_eq_u32_e64 s[4:5], 0, v16
	s_ashr_i32 s74, s1, 31
	s_ashr_i32 s75, s0, 31
	v_mov_b32_e32 v135, v193
	v_lshl_add_u32 v136, v10, 1, v0
	v_mov_b32_e32 v137, v193
	v_add_u32_e32 v147, s18, v18
	s_barrier
	s_branch .LBB0_1114

; #define PG8_STAGE(bufoff, gbase, voff) do { _Pragma("unroll") for (int _i = 0; _i < 2; ++_i) \
;         __builtin_amdgcn_global_load_lds((const unsigned*)((const char*)(gbase) + (voff)[_i]), (PG8_LAS unsigned*)(lds + (bufoff) + ldsw + _i * 8192), 16, 0, 0); } while (0)
; #define PG8_WAIT_V(n) asm volatile("s_waitcnt vmcnt(" #n ")" ::: "memory")
; #define PG8_BAR __builtin_amdgcn_s_barrier()
; template <class Epi, class Sched, bool ALIGN_EPI = false, bool SP2 = false>
; __device__ __forceinline__ void gemm_phase(PG8_LAS unsigned char* lds, const Gemm g, const Sched& S, const Epi& E) {
;     ...
;         PG8_STAGE(PG8_SB(0, 0), cB, voffB); PG8_STAGE(PG8_SB(0, 1), cB + hstepB, voffB); PG8_STAGE(PG8_SA(0, 0), cA, voffA); PG8_STAGE(PG8_SA(0, 1), cA + hstepA, voffA);
;         if (wr == 1) PG8_BAR;
;         PG8_WAIT_V(2); PG8_BAR;
;         PG8_STAGE(PG8_SB(1, 0), cB + kstep, voffB); PG8_STAGE(PG8_SA(1, 0), cA + kstep, voffA); PG8_STAGE(PG8_SB(1, 1), cB + hstepB + kstep, voffB);
;         PG8_WAIT_V(6); PG8_BAR;
; __global__ void __launch_bounds__(NTHREADS, 2) mega_fwd(Args args) {
;     ...
;             pg8::Gemm g{XB, (const bf16*)(ws + WS_W2A), M, 2 * FFH, DM, DM, DM}; pg8::StaticOrder S; S.init(M, 2 * FFH, G_, bx_);
;             EpiSwiglu E{ACT, SSQ};
;             pg8::gemm_phase<EpiSwiglu, pg8::StaticOrder, true, true>(ldsp, g, S, E);
.LBB0_1215:
	v_bfe_u32 v18, v14, 4, 2
	s_sext_i32_i16 s66, s8
	s_add_u32 s8, s4, 0x7a00000
	v_and_b32_e32 v15, 15, v14
	v_lshlrev_b32_e32 v16, 4, v18
	v_lshlrev_b32_e32 v14, 2, v14
	s_addc_u32 s9, s5, 0
	v_lshl_or_b32 v148, s2, 6, v15
	v_lshl_or_b32 v15, v15, 6, v16
	s_lshl_b32 s2, s2, 13
	v_and_b32_e32 v14, 32, v14
	v_bitop3_b32 v19, v15, s2, v14 bitop3:0xde
	s_lshl_b32 s2, s13, 5
	s_add_i32 s44, s12, 0x18000
	s_and_b32 s2, s2, 0x60
	s_add_i32 s45, s44, s11
	s_lshl_b32 s13, s2, 7
	v_lshl_add_u64 v[6:7], v[6:7], 0, s[76:77]
	s_mov_b32 m0, s45
	s_add_i32 s48, s45, 0x2000
	s_add_i32 s49, s40, 0x8000
	s_add_i32 s50, s40, 0xa000
	global_load_lds_dwordx4 v[6:7], off
	v_lshl_add_u64 v[4:5], v[4:5], 0, s[76:77]
	s_mov_b32 m0, s48
	s_add_u32 s14, s22, 0x40080
	global_load_lds_dwordx4 v[4:5], off
	v_lshl_add_u64 v[0:1], v[0:1], 0, s[76:77]
	s_mov_b32 m0, s49
	s_addc_u32 s15, s23, 0
	s_add_i32 s51, s12, 0x1c000
	global_load_lds_dwordx4 v[0:1], off
	v_lshl_add_u64 v[0:1], v[2:3], 0, s[76:77]
	s_mov_b32 m0, s50
	s_add_i32 s60, s51, s11
	global_load_lds_dwordx4 v[0:1], off
	v_lshl_add_u64 v[0:1], s[14:15], 0, v[192:193]
	s_mov_b32 m0, s60
	s_add_i32 s61, s60, 0x2000
	global_load_lds_dwordx4 v[0:1], off
	v_lshl_add_u64 v[0:1], s[14:15], 0, v[128:129]
	s_mov_b32 m0, s61
	v_mov_b32_e32 v17, v193
	global_load_lds_dwordx4 v[0:1], off
	s_waitcnt vmcnt(8)
	s_barrier
	v_lshl_add_u64 v[0:1], s[4:5], 0, v[16:17]
	s_mov_b64 s[4:5], 0x3600000
	v_lshl_add_u64 v[134:135], v[0:1], 0, s[4:5]
	v_lshlrev_b32_e32 v0, 14, v8
	v_and_b32_e32 v0, 0xffff8000, v0
	v_lshl_add_u32 v0, v9, 11, v0
	v_and_b32_e32 v1, 1, v8
	v_lshl_or_b32 v0, v1, 6, v0
	v_lshl_add_u32 v136, v10, 1, v0
	v_lshlrev_b32_e32 v0, 14, v12
	v_and_b32_e32 v0, 0xffff8000, v0
	s_waitcnt vmcnt(6)
	v_lshl_add_u32 v0, v11, 11, v0
	v_and_b32_e32 v1, 1, v12
	s_cmpk_lt_u32 s10, 0x100
	v_lshl_or_b32 v0, v1, 6, v0
	v_bitop3_b32 v149, v15, s13, v14 bitop3:0xde
	s_cselect_b64 s[10:11], -1, 0
	s_ashr_i32 s64, s1, 31
	v_lshl_or_b32 v150, v18, 3, s2
	v_mov_b32_e32 v137, v193
	v_lshl_add_u32 v138, v13, 1, v0
	v_mov_b32_e32 v139, v193
	s_mov_b32 s65, 0
	v_add_u32_e32 v151, s12, v19
	s_barrier
	s_branch .LBB0_1218
